# plus: idx relu canonicalize+max fused; MoE-up SwiGLU epilogue: two constant multiplies fused into one, (lin+1)*t as one fma
# speedup vs baseline: 1.0190x; 1.0044x over previous
.LBB0_572:
	ds_read_b128 v[18:21], v164
	ds_read_b128 v[166:169], v164 offset:32
	ds_read_b128 v[170:173], v164 offset:64
	ds_read_b128 v[174:177], v164 offset:96
	ds_read_b128 v[180:183], v164 offset:128
	ds_read_b128 v[184:187], v164 offset:160
	ds_read_b128 v[188:191], v164 offset:192
	ds_read_b128 v[192:195], v164 offset:224
	s_waitcnt lgkmcnt(7)
	v_mfma_f32_32x32x16_bf16 v[2:17], v[34:37], v[18:21], 0
	s_and_b32 s2, s15, 0xc0
	v_lshl_add_u32 v178, s2, 2, v157
	s_add_i32 s2, s1, -2
	s_cmp_ge_u32 s2, s29
	s_waitcnt lgkmcnt(6)
	v_mfma_f32_32x32x16_bf16 v[2:17], v[38:41], v[166:169], v[2:17]
	s_waitcnt lgkmcnt(5)
	v_mfma_f32_32x32x16_bf16 v[2:17], v[42:45], v[170:173], v[2:17]
	s_waitcnt lgkmcnt(4)
	v_mfma_f32_32x32x16_bf16 v[2:17], v[46:49], v[174:177], v[2:17]
	v_mfma_f32_32x32x16_bf16 v[18:33], v[82:85], v[18:21], 0
	s_waitcnt lgkmcnt(3)
	v_mfma_f32_32x32x16_bf16 v[2:17], v[50:53], v[180:183], v[2:17]
	v_mfma_f32_32x32x16_bf16 v[18:33], v[86:89], v[166:169], v[18:33]
	s_waitcnt lgkmcnt(2)
	v_mfma_f32_32x32x16_bf16 v[2:17], v[54:57], v[184:187], v[2:17]
	v_mfma_f32_32x32x16_bf16 v[18:33], v[90:93], v[170:173], v[18:33]
	s_waitcnt lgkmcnt(1)
	v_mfma_f32_32x32x16_bf16 v[2:17], v[58:61], v[188:191], v[2:17]
	v_mfma_f32_32x32x16_bf16 v[18:33], v[94:97], v[174:177], v[18:33]
	s_waitcnt lgkmcnt(0)
	v_mfma_f32_32x32x16_bf16 v[2:17], v[62:65], v[192:195], v[2:17]
	v_mfma_f32_32x32x16_bf16 v[18:33], v[98:101], v[180:183], v[18:33]
	s_nop 10
	v_max_f32_e32 v2, 0, v2
	v_max_f32_e32 v3, 0, v3
	v_fma_f32 v2, v2, v66, 0
	v_fmac_f32_e32 v2, v3, v67
	v_max_f32_e32 v3, 0, v4
	v_fmac_f32_e32 v2, v3, v68
	v_max_f32_e32 v3, 0, v5
	v_fmac_f32_e32 v2, v3, v69
	v_max_f32_e32 v3, v6, v6
	v_mfma_f32_32x32x16_bf16 v[18:33], v[102:105], v[184:187], v[18:33]
	v_max_f32_e32 v3, 0, v3
	v_fmac_f32_e32 v2, v3, v70
	v_max_f32_e32 v3, 0, v7
	v_fmac_f32_e32 v2, v3, v71
	v_max_f32_e32 v3, 0, v8
	v_fmac_f32_e32 v2, v3, v72
	v_max_f32_e32 v3, 0, v9
	v_fmac_f32_e32 v2, v3, v73
	v_max_f32_e32 v3, v10, v10
	v_mfma_f32_32x32x16_bf16 v[18:33], v[106:109], v[188:191], v[18:33]
	v_max_f32_e32 v3, 0, v3
	v_fmac_f32_e32 v2, v3, v78
	v_max_f32_e32 v3, 0, v11
	v_fmac_f32_e32 v2, v3, v79
	v_max_f32_e32 v3, 0, v12
	v_fmac_f32_e32 v2, v3, v80
	v_max_f32_e32 v3, 0, v13
	v_fmac_f32_e32 v2, v3, v81
	v_max_f32_e32 v3, v14, v14
	v_mfma_f32_32x32x16_bf16 v[18:33], v[110:113], v[192:195], v[18:33]
	v_max_f32_e32 v3, 0, v3
	v_fmac_f32_e32 v2, v3, v74
	v_max_f32_e32 v3, 0, v15
	v_fmac_f32_e32 v2, v3, v75
	v_max_f32_e32 v3, 0, v16
	v_fmac_f32_e32 v2, v3, v76
	v_max_f32_e32 v3, 0, v17
	v_fmac_f32_e32 v2, v3, v77
	s_nop 4
	v_max_f32_e32 v3, 0, v18
	v_max_f32_e32 v4, v19, v19
	v_fma_f32 v3, v3, v114, 0
	v_max_f32_e32 v4, 0, v4
	v_fmac_f32_e32 v3, v4, v115
	v_max_f32_e32 v4, 0, v20
	v_fmac_f32_e32 v3, v4, v116
	v_max_f32_e32 v4, 0, v21
	v_fmac_f32_e32 v3, v4, v117
	v_max_f32_e32 v4, 0, v22
	v_fmac_f32_e32 v3, v4, v118
	v_max_f32_e32 v4, 0, v23
	v_fmac_f32_e32 v3, v4, v119
	v_max_f32_e32 v4, 0, v24
	v_fmac_f32_e32 v3, v4, v120
	v_max_f32_e32 v4, 0, v25
	v_fmac_f32_e32 v3, v4, v121
	v_max_f32_e32 v4, 0, v26
	v_fmac_f32_e32 v3, v4, v122
	v_max_f32_e32 v4, 0, v27
	v_fmac_f32_e32 v3, v4, v123
	v_max_f32_e32 v4, 0, v28
	v_fmac_f32_e32 v3, v4, v124
	v_max_f32_e32 v4, 0, v29
	v_fmac_f32_e32 v3, v4, v125
	v_max_f32_e32 v4, 0, v30
	v_fmac_f32_e32 v3, v4, v126
	v_max_f32_e32 v4, 0, v31
	v_fmac_f32_e32 v3, v4, v127
	v_max_f32_e32 v4, 0, v32
	v_fmac_f32_e32 v3, v4, v128
	v_max_f32_e32 v4, 0, v33
	v_fmac_f32_e32 v3, v4, v129
	ds_write2st64_b32 v178, v2, v3 offset0:128 offset1:136
	s_cbranch_scc1 .LBB0_578
	s_mov_b64 s[26:27], -1
	s_and_b64 vcc, exec, s[24:25]
	s_cbranch_vccz .LBB0_575
	s_waitcnt vmcnt(0)
	s_mov_b64 s[26:27], 0

.LBB0_580:
	ds_read_b128 v[18:21], v164 offset:8704
	ds_read_b128 v[166:169], v164 offset:8736
	ds_read_b128 v[170:173], v164 offset:8768
	ds_read_b128 v[174:177], v164 offset:8800
	ds_read_b128 v[180:183], v164 offset:8832
	ds_read_b128 v[184:187], v164 offset:8864
	ds_read_b128 v[188:191], v164 offset:8896
	ds_read_b128 v[192:195], v164 offset:8928
	s_waitcnt lgkmcnt(7)
	v_mfma_f32_32x32x16_bf16 v[2:17], v[34:37], v[18:21], 0
	s_add_i32 s26, s15, 32
	s_and_b32 s26, s26, 0xe0
	v_lshl_add_u32 v178, s26, 2, v157
	s_andn2_b64 vcc, exec, s[22:23]
	s_waitcnt lgkmcnt(6)
	v_mfma_f32_32x32x16_bf16 v[2:17], v[38:41], v[166:169], v[2:17]
	s_waitcnt lgkmcnt(5)
	v_mfma_f32_32x32x16_bf16 v[2:17], v[42:45], v[170:173], v[2:17]
	s_waitcnt lgkmcnt(4)
	v_mfma_f32_32x32x16_bf16 v[2:17], v[46:49], v[174:177], v[2:17]
	v_mfma_f32_32x32x16_bf16 v[18:33], v[82:85], v[18:21], 0
	s_waitcnt lgkmcnt(3)
	v_mfma_f32_32x32x16_bf16 v[2:17], v[50:53], v[180:183], v[2:17]
	v_mfma_f32_32x32x16_bf16 v[18:33], v[86:89], v[166:169], v[18:33]
	s_waitcnt lgkmcnt(2)
	v_mfma_f32_32x32x16_bf16 v[2:17], v[54:57], v[184:187], v[2:17]
	v_mfma_f32_32x32x16_bf16 v[18:33], v[90:93], v[170:173], v[18:33]
	s_waitcnt lgkmcnt(1)
	v_mfma_f32_32x32x16_bf16 v[2:17], v[58:61], v[188:191], v[2:17]
	v_mfma_f32_32x32x16_bf16 v[18:33], v[94:97], v[174:177], v[18:33]
	s_waitcnt lgkmcnt(0)
	v_mfma_f32_32x32x16_bf16 v[2:17], v[62:65], v[192:195], v[2:17]
	v_mfma_f32_32x32x16_bf16 v[18:33], v[98:101], v[180:183], v[18:33]
	s_nop 10
	v_max_f32_e32 v2, 0, v2
	v_max_f32_e32 v3, 0, v3
	v_fma_f32 v2, v2, v66, 0
	v_fmac_f32_e32 v2, v3, v67
	v_max_f32_e32 v3, 0, v4
	v_fmac_f32_e32 v2, v3, v68
	v_max_f32_e32 v3, 0, v5
	v_fmac_f32_e32 v2, v3, v69
	v_max_f32_e32 v3, v6, v6
	v_mfma_f32_32x32x16_bf16 v[18:33], v[102:105], v[184:187], v[18:33]
	v_max_f32_e32 v3, 0, v3
	v_fmac_f32_e32 v2, v3, v70
	v_max_f32_e32 v3, 0, v7
	v_fmac_f32_e32 v2, v3, v71
	v_max_f32_e32 v3, 0, v8
	v_fmac_f32_e32 v2, v3, v72
	v_max_f32_e32 v3, 0, v9
	v_fmac_f32_e32 v2, v3, v73
	v_max_f32_e32 v3, v10, v10
	v_mfma_f32_32x32x16_bf16 v[18:33], v[106:109], v[188:191], v[18:33]
	v_max_f32_e32 v3, 0, v3
	v_fmac_f32_e32 v2, v3, v78
	v_max_f32_e32 v3, 0, v11
	v_fmac_f32_e32 v2, v3, v79
	v_max_f32_e32 v3, 0, v12
	v_fmac_f32_e32 v2, v3, v80
	v_max_f32_e32 v3, 0, v13
	v_fmac_f32_e32 v2, v3, v81
	v_max_f32_e32 v3, v14, v14
	v_mfma_f32_32x32x16_bf16 v[18:33], v[110:113], v[192:195], v[18:33]
	v_max_f32_e32 v3, 0, v3
	v_fmac_f32_e32 v2, v3, v74
	v_max_f32_e32 v3, 0, v15
	v_fmac_f32_e32 v2, v3, v75
	v_max_f32_e32 v3, 0, v16
	v_fmac_f32_e32 v2, v3, v76
	v_max_f32_e32 v3, 0, v17
	v_fmac_f32_e32 v2, v3, v77
	s_nop 4
	v_max_f32_e32 v3, 0, v18
	v_max_f32_e32 v4, v19, v19
	v_fma_f32 v3, v3, v114, 0
	v_max_f32_e32 v4, 0, v4
	v_fmac_f32_e32 v3, v4, v115
	v_max_f32_e32 v4, 0, v20
	v_fmac_f32_e32 v3, v4, v116
	v_max_f32_e32 v4, 0, v21
	v_fmac_f32_e32 v3, v4, v117
	v_max_f32_e32 v4, 0, v22
	v_fmac_f32_e32 v3, v4, v118
	v_max_f32_e32 v4, 0, v23
	v_fmac_f32_e32 v3, v4, v119
	v_max_f32_e32 v4, 0, v24
	v_fmac_f32_e32 v3, v4, v120
	v_max_f32_e32 v4, 0, v25
	v_fmac_f32_e32 v3, v4, v121
	v_max_f32_e32 v4, 0, v26
	v_fmac_f32_e32 v3, v4, v122
	v_max_f32_e32 v4, 0, v27
	v_fmac_f32_e32 v3, v4, v123
	v_max_f32_e32 v4, 0, v28
	v_fmac_f32_e32 v3, v4, v124
	v_max_f32_e32 v4, 0, v29
	v_fmac_f32_e32 v3, v4, v125
	v_max_f32_e32 v4, 0, v30
	v_fmac_f32_e32 v3, v4, v126
	v_max_f32_e32 v4, 0, v31
	v_fmac_f32_e32 v3, v4, v127
	v_max_f32_e32 v4, 0, v32
	v_fmac_f32_e32 v3, v4, v128
	v_max_f32_e32 v4, 0, v33
	v_fmac_f32_e32 v3, v4, v129
	ds_write2st64_b32 v178, v2, v3 offset0:128 offset1:136
	s_cbranch_vccnz .LBB0_586
	s_mov_b64 s[22:23], -1
	s_and_b64 vcc, exec, s[24:25]
	s_cbranch_vccz .LBB0_583
	s_waitcnt vmcnt(0)
	s_mov_b64 s[22:23], 0

.LBB0_1590:
	v_fmamk_f32 v3, v206, 0x3d000000, v66
	v_min_f32_e32 v3, 0x40e00000, v3
	v_mul_f32_e32 v4, 0xc01d265f, v3
	v_exp_f32_e32 v7, v4
	v_fmamk_f32 v8, v207, 0x3d000000, v67
	v_min_f32_e32 v8, 0x40e00000, v8
	v_mul_f32_e32 v9, 0xc01d265f, v8
	v_add_f32_e32 v7, 1.0, v7
	v_rcp_f32_e32 v7, v7
	v_exp_f32_e32 v9, v9
	v_fmamk_f32 v10, v209, 0x3d000000, v69
	v_min_f32_e32 v10, 0x40e00000, v10
	v_mul_f32_e32 v3, v3, v7
	v_add_f32_e32 v7, 1.0, v9
	v_rcp_f32_e32 v7, v7
	v_mul_f32_e32 v11, 0xc01d265f, v10
	v_exp_f32_e32 v11, v11
	v_mul_f32_e32 v7, v8, v7
	v_fmamk_f32 v8, v208, 0x3d000000, v68
	v_min_f32_e32 v8, 0x40e00000, v8
	v_mul_f32_e32 v9, 0xc01d265f, v8
	v_exp_f32_e32 v9, v9
	s_lshl_b32 s0, s0, 8
	v_mbcnt_lo_u32_b32 v2, -1, 0
	v_mbcnt_hi_u32_b32 v2, -1, v2
	s_add_i32 s0, s0, s63
	v_add_f32_e32 v9, 1.0, v9
	v_rcp_f32_e32 v9, v9
	v_and_or_b32 v6, v2, 15, s0
	v_ashrrev_i32_e32 v2, 1, v2
	s_or_b32 s0, s44, s64
	v_and_b32_e32 v2, -8, v2
	v_mul_f32_e32 v8, v8, v9
	v_add_f32_e32 v9, 1.0, v11
	v_add_u32_e32 v4, s0, v2
	v_fmamk_f32 v2, v202, 0x3d000000, v74
	v_rcp_f32_e32 v9, v9
	v_med3_f32 v2, v2, s69, v247
	v_fma_f32 v2, v3, v2, v3
	v_fmamk_f32 v3, v203, 0x3d000000, v75
	v_med3_f32 v3, v3, s69, v247
	v_mul_f32_e32 v9, v10, v9
	v_fmamk_f32 v10, v198, 0x3d000000, v70
	v_min_f32_e32 v10, 0x40e00000, v10
	v_fma_f32 v3, v7, v3, v7
	v_fmamk_f32 v7, v204, 0x3d000000, v76
	v_mul_f32_e32 v11, 0xc01d265f, v10
	v_med3_f32 v7, v7, s69, v247
	v_exp_f32_e32 v11, v11
	v_fma_f32 v7, v8, v7, v8
	v_fmamk_f32 v8, v205, 0x3d000000, v77
	v_med3_f32 v8, v8, s69, v247
	v_fma_f32 v12, v9, v8, v9
	v_add_f32_e32 v9, 1.0, v11
	v_fmamk_f32 v11, v199, 0x3d000000, v71
	v_min_f32_e32 v11, 0x40e00000, v11
	v_mul_f32_e32 v13, 0xc01d265f, v11
	v_rcp_f32_e32 v9, v9
	v_exp_f32_e32 v13, v13
	v_fmamk_f32 v8, v194, 0x3d000000, v78
	v_med3_f32 v8, v8, s69, v247
	v_mul_f32_e32 v9, v10, v9
	v_add_f32_e32 v10, 1.0, v13
	v_rcp_f32_e32 v10, v10
	v_fma_f32 v13, v9, v8, v9
	v_fmamk_f32 v8, v195, 0x3d000000, v79
	v_mul_f32_e32 v9, v11, v10
	v_fmamk_f32 v10, v200, 0x3d000000, v72
	v_min_f32_e32 v10, 0x40e00000, v10
	v_mul_f32_e32 v11, 0xc01d265f, v10
	v_exp_f32_e32 v11, v11
	v_med3_f32 v8, v8, s69, v247
	v_fma_f32 v14, v9, v8, v9
	v_add_f32_e32 v9, 1.0, v11
	v_fmamk_f32 v11, v201, 0x3d000000, v73
	v_min_f32_e32 v11, 0x40e00000, v11
	v_mul_f32_e32 v15, 0xc01d265f, v11
	v_rcp_f32_e32 v9, v9
	v_exp_f32_e32 v15, v15
	v_fmamk_f32 v8, v196, 0x3d000000, v80
	v_med3_f32 v8, v8, s69, v247
	v_mul_f32_e32 v9, v10, v9
	v_add_f32_e32 v10, 1.0, v15
	v_fma_f32 v15, v9, v8, v9
	v_fmamk_f32 v8, v197, 0x3d000000, v81
	v_rcp_f32_e32 v10, v10
	v_med3_f32 v16, v8, s69, v247
	v_mov_b32_e32 v8, v217
	v_cvt_pk_fp8_f32 v8, v2, v3
	v_mov_b32_e32 v9, v217
	v_cvt_pk_fp8_f32 v9, v13, v14
	v_mul_f32_e32 v10, v11, v10
	v_fma_f32 v2, v10, v16, v10
	v_cvt_pk_fp8_f32 v8, v7, v12 op_sel:[0,0,1]
	v_ashrrev_i32_e32 v7, 31, v6
	v_cvt_pk_fp8_f32 v9, v15, v2 op_sel:[0,0,1]
	v_lshlrev_b64 v[2:3], 11, v[6:7]
	v_fmamk_f32 v7, v190, 0x3d000000, v66
	v_min_f32_e32 v7, 0x40e00000, v7
	v_mul_f32_e32 v10, 0xc01d265f, v7
	v_exp_f32_e32 v10, v10
	v_ashrrev_i32_e32 v5, 31, v4
	v_lshl_add_u64 v[2:3], s[20:21], 0, v[2:3]
	v_lshl_add_u64 v[2:3], v[2:3], 0, v[4:5]
	global_store_dwordx2 v[2:3], v[8:9], off
	v_add_f32_e32 v9, 1.0, v10
	v_fmamk_f32 v10, v191, 0x3d000000, v67
	v_min_f32_e32 v10, 0x40e00000, v10
	v_mul_f32_e32 v11, 0xc01d265f, v10
	v_rcp_f32_e32 v9, v9
	v_exp_f32_e32 v11, v11
	v_fmamk_f32 v12, v193, 0x3d000000, v69
	v_min_f32_e32 v12, 0x40e00000, v12
	v_mul_f32_e32 v7, v7, v9
	v_add_f32_e32 v9, 1.0, v11
	v_rcp_f32_e32 v9, v9
	v_mul_f32_e32 v13, 0xc01d265f, v12
	v_exp_f32_e32 v13, v13
	v_mul_f32_e32 v9, v10, v9
	v_fmamk_f32 v10, v192, 0x3d000000, v68
	v_min_f32_e32 v10, 0x40e00000, v10
	v_mul_f32_e32 v11, 0xc01d265f, v10
	v_exp_f32_e32 v11, v11
	v_fmamk_f32 v14, v183, 0x3d000000, v71
	v_min_f32_e32 v14, 0x40e00000, v14
	v_mul_f32_e32 v15, 0xc01d265f, v14
	v_add_f32_e32 v11, 1.0, v11
	v_rcp_f32_e32 v11, v11
	v_exp_f32_e32 v15, v15
	v_fmamk_f32 v8, v186, 0x3d000000, v74
	v_mul_f32_e32 v10, v10, v11
	v_add_f32_e32 v11, 1.0, v13
	v_rcp_f32_e32 v11, v11
	v_med3_f32 v8, v8, s69, v247
	v_fma_f32 v7, v7, v8, v7
	v_mul_f32_e32 v11, v12, v11
	v_fmamk_f32 v12, v182, 0x3d000000, v70
	v_min_f32_e32 v12, 0x40e00000, v12
	v_mul_f32_e32 v13, 0xc01d265f, v12
	v_exp_f32_e32 v13, v13
	v_fmamk_f32 v8, v187, 0x3d000000, v75
	v_med3_f32 v8, v8, s69, v247
	v_add_f32_e32 v13, 1.0, v13
	v_rcp_f32_e32 v13, v13
	v_fma_f32 v9, v9, v8, v9
	v_fmamk_f32 v8, v188, 0x3d000000, v76
	v_med3_f32 v8, v8, s69, v247
	v_mul_f32_e32 v12, v12, v13
	v_add_f32_e32 v13, 1.0, v15
	v_rcp_f32_e32 v13, v13
	v_fma_f32 v10, v10, v8, v10
	v_fmamk_f32 v8, v189, 0x3d000000, v77
	v_mul_f32_e32 v13, v14, v13
	v_fmamk_f32 v14, v184, 0x3d000000, v72
	v_min_f32_e32 v14, 0x40e00000, v14
	v_mul_f32_e32 v15, 0xc01d265f, v14
	v_med3_f32 v8, v8, s69, v247
	v_exp_f32_e32 v15, v15
	v_fma_f32 v11, v11, v8, v11
	v_fmamk_f32 v8, v178, 0x3d000000, v78
	v_med3_f32 v8, v8, s69, v247
	v_fmamk_f32 v16, v185, 0x3d000000, v73
	v_min_f32_e32 v16, 0x40e00000, v16
	v_fma_f32 v12, v12, v8, v12
	v_fmamk_f32 v8, v179, 0x3d000000, v79
	v_add_f32_e32 v15, 1.0, v15
	v_mul_f32_e32 v17, 0xc01d265f, v16
	v_med3_f32 v8, v8, s69, v247
	v_rcp_f32_e32 v15, v15
	v_exp_f32_e32 v17, v17
	v_fma_f32 v13, v13, v8, v13
	v_fmamk_f32 v8, v180, 0x3d000000, v80
	v_med3_f32 v8, v8, s69, v247
	v_mul_f32_e32 v14, v14, v15
	v_add_f32_e32 v15, 1.0, v17
	v_fma_f32 v14, v14, v8, v14
	v_fmamk_f32 v8, v181, 0x3d000000, v81
	v_rcp_f32_e32 v15, v15
	v_med3_f32 v17, v8, s69, v247
	v_mov_b32_e32 v8, v217
	v_cvt_pk_fp8_f32 v8, v7, v9
	v_mov_b32_e32 v9, v217
	v_cvt_pk_fp8_f32 v9, v12, v13
	v_mul_f32_e32 v15, v16, v15
	v_fma_f32 v7, v15, v17, v15
	v_cvt_pk_fp8_f32 v8, v10, v11 op_sel:[0,0,1]
	v_cvt_pk_fp8_f32 v9, v14, v7 op_sel:[0,0,1]
	v_or_b32_e32 v10, 16, v6
	v_fmamk_f32 v7, v174, 0x3d000000, v66
	v_ashrrev_i32_e32 v11, 31, v10
	v_min_f32_e32 v7, 0x40e00000, v7
	v_lshlrev_b64 v[10:11], 11, v[10:11]
	v_mul_f32_e32 v12, 0xc01d265f, v7
	v_lshl_add_u64 v[10:11], s[20:21], 0, v[10:11]
	v_exp_f32_e32 v12, v12
	v_lshl_add_u64 v[10:11], v[10:11], 0, v[4:5]
	global_store_dwordx2 v[10:11], v[8:9], off
	v_fmamk_f32 v10, v175, 0x3d000000, v67
	v_min_f32_e32 v10, 0x40e00000, v10
	v_mul_f32_e32 v11, 0xc01d265f, v10
	v_add_f32_e32 v9, 1.0, v12
	v_rcp_f32_e32 v9, v9
	v_exp_f32_e32 v11, v11
	v_fmamk_f32 v12, v177, 0x3d000000, v69
	v_min_f32_e32 v12, 0x40e00000, v12
	v_mul_f32_e32 v7, v7, v9
	v_add_f32_e32 v9, 1.0, v11
	v_rcp_f32_e32 v9, v9
	v_mul_f32_e32 v13, 0xc01d265f, v12
	v_exp_f32_e32 v13, v13
	v_mul_f32_e32 v9, v10, v9
	v_fmamk_f32 v10, v176, 0x3d000000, v68
	v_min_f32_e32 v10, 0x40e00000, v10
	v_mul_f32_e32 v11, 0xc01d265f, v10
	v_exp_f32_e32 v11, v11
	v_fmamk_f32 v14, v167, 0x3d000000, v71
	v_min_f32_e32 v14, 0x40e00000, v14
	v_mul_f32_e32 v15, 0xc01d265f, v14
	v_add_f32_e32 v11, 1.0, v11
	v_rcp_f32_e32 v11, v11
	v_exp_f32_e32 v15, v15
	v_fmamk_f32 v8, v170, 0x3d000000, v74
	v_mul_f32_e32 v10, v10, v11
	v_add_f32_e32 v11, 1.0, v13
	v_rcp_f32_e32 v11, v11
	v_med3_f32 v8, v8, s69, v247
	v_fma_f32 v7, v7, v8, v7
	v_mul_f32_e32 v11, v12, v11
	v_fmamk_f32 v12, v166, 0x3d000000, v70
	v_min_f32_e32 v12, 0x40e00000, v12
	v_mul_f32_e32 v13, 0xc01d265f, v12
	v_exp_f32_e32 v13, v13
	v_fmamk_f32 v8, v171, 0x3d000000, v75
	v_med3_f32 v8, v8, s69, v247
	v_add_f32_e32 v13, 1.0, v13
	v_rcp_f32_e32 v13, v13
	v_fma_f32 v9, v9, v8, v9
	v_fmamk_f32 v8, v172, 0x3d000000, v76
	v_med3_f32 v8, v8, s69, v247
	v_mul_f32_e32 v12, v12, v13
	v_add_f32_e32 v13, 1.0, v15
	v_rcp_f32_e32 v13, v13
	v_fma_f32 v10, v10, v8, v10
	v_fmamk_f32 v8, v173, 0x3d000000, v77
	v_mul_f32_e32 v13, v14, v13
	v_fmamk_f32 v14, v168, 0x3d000000, v72
	v_min_f32_e32 v14, 0x40e00000, v14
	v_mul_f32_e32 v15, 0xc01d265f, v14
	v_med3_f32 v8, v8, s69, v247
	v_exp_f32_e32 v15, v15
	v_fma_f32 v11, v11, v8, v11
	v_fmamk_f32 v8, v162, 0x3d000000, v78
	v_med3_f32 v8, v8, s69, v247
	v_fmamk_f32 v16, v169, 0x3d000000, v73
	v_min_f32_e32 v16, 0x40e00000, v16
	v_fma_f32 v12, v12, v8, v12
	v_fmamk_f32 v8, v163, 0x3d000000, v79
	v_add_f32_e32 v15, 1.0, v15
	v_mul_f32_e32 v17, 0xc01d265f, v16
	v_med3_f32 v8, v8, s69, v247
	v_rcp_f32_e32 v15, v15
	v_exp_f32_e32 v17, v17
	v_fma_f32 v13, v13, v8, v13
	v_fmamk_f32 v8, v164, 0x3d000000, v80
	v_med3_f32 v8, v8, s69, v247
	v_mul_f32_e32 v14, v14, v15
	v_add_f32_e32 v15, 1.0, v17
	v_fma_f32 v14, v14, v8, v14
	v_fmamk_f32 v8, v165, 0x3d000000, v81
	v_rcp_f32_e32 v15, v15
	v_med3_f32 v17, v8, s69, v247
	v_mov_b32_e32 v8, v217
	v_cvt_pk_fp8_f32 v8, v7, v9
	v_mov_b32_e32 v9, v217
	v_cvt_pk_fp8_f32 v9, v12, v13
	v_mul_f32_e32 v15, v16, v15
	v_fma_f32 v7, v15, v17, v15
	v_cvt_pk_fp8_f32 v8, v10, v11 op_sel:[0,0,1]
	v_cvt_pk_fp8_f32 v9, v14, v7 op_sel:[0,0,1]
	v_or_b32_e32 v10, 32, v6
	v_fmamk_f32 v7, v158, 0x3d000000, v66
	v_ashrrev_i32_e32 v11, 31, v10
	v_min_f32_e32 v7, 0x40e00000, v7
	v_lshlrev_b64 v[10:11], 11, v[10:11]
	v_mul_f32_e32 v12, 0xc01d265f, v7
	v_lshl_add_u64 v[10:11], s[20:21], 0, v[10:11]
	v_exp_f32_e32 v12, v12
	v_lshl_add_u64 v[10:11], v[10:11], 0, v[4:5]
	global_store_dwordx2 v[10:11], v[8:9], off
	v_fmamk_f32 v10, v159, 0x3d000000, v67
	v_min_f32_e32 v10, 0x40e00000, v10
	v_mul_f32_e32 v11, 0xc01d265f, v10
	v_add_f32_e32 v9, 1.0, v12
	v_rcp_f32_e32 v9, v9
	v_exp_f32_e32 v11, v11
	v_fmamk_f32 v12, v161, 0x3d000000, v69
	v_min_f32_e32 v12, 0x40e00000, v12
	v_mul_f32_e32 v7, v7, v9
	v_add_f32_e32 v9, 1.0, v11
	v_rcp_f32_e32 v9, v9
	v_mul_f32_e32 v13, 0xc01d265f, v12
	v_exp_f32_e32 v13, v13
	v_mul_f32_e32 v9, v10, v9
	v_fmamk_f32 v10, v160, 0x3d000000, v68
	v_min_f32_e32 v10, 0x40e00000, v10
	v_mul_f32_e32 v11, 0xc01d265f, v10
	v_exp_f32_e32 v11, v11
	v_fmamk_f32 v14, v151, 0x3d000000, v71
	v_min_f32_e32 v14, 0x40e00000, v14
	v_mul_f32_e32 v15, 0xc01d265f, v14
	v_add_f32_e32 v11, 1.0, v11
	v_rcp_f32_e32 v11, v11
	v_exp_f32_e32 v15, v15
	v_fmamk_f32 v8, v154, 0x3d000000, v74
	v_mul_f32_e32 v10, v10, v11
	v_add_f32_e32 v11, 1.0, v13
	v_rcp_f32_e32 v11, v11
	v_med3_f32 v8, v8, s69, v247
	v_fma_f32 v7, v7, v8, v7
	v_mul_f32_e32 v11, v12, v11
	v_fmamk_f32 v12, v150, 0x3d000000, v70
	v_min_f32_e32 v12, 0x40e00000, v12
	v_mul_f32_e32 v13, 0xc01d265f, v12
	v_exp_f32_e32 v13, v13
	v_fmamk_f32 v8, v155, 0x3d000000, v75
	v_med3_f32 v8, v8, s69, v247
	v_add_f32_e32 v13, 1.0, v13
	v_rcp_f32_e32 v13, v13
	v_fma_f32 v9, v9, v8, v9
	v_fmamk_f32 v8, v156, 0x3d000000, v76
	v_med3_f32 v8, v8, s69, v247
	v_mul_f32_e32 v12, v12, v13
	v_add_f32_e32 v13, 1.0, v15
	v_rcp_f32_e32 v13, v13
	v_fma_f32 v10, v10, v8, v10
	v_fmamk_f32 v8, v157, 0x3d000000, v77
	v_mul_f32_e32 v13, v14, v13
	v_fmamk_f32 v14, v152, 0x3d000000, v72
	v_min_f32_e32 v14, 0x40e00000, v14
	v_mul_f32_e32 v15, 0xc01d265f, v14
	v_med3_f32 v8, v8, s69, v247
	v_exp_f32_e32 v15, v15
	v_fma_f32 v11, v11, v8, v11
	v_fmamk_f32 v8, v146, 0x3d000000, v78
	v_med3_f32 v8, v8, s69, v247
	v_fmamk_f32 v16, v153, 0x3d000000, v73
	v_min_f32_e32 v16, 0x40e00000, v16
	v_fma_f32 v12, v12, v8, v12
	v_fmamk_f32 v8, v147, 0x3d000000, v79
	v_add_f32_e32 v15, 1.0, v15
	v_mul_f32_e32 v17, 0xc01d265f, v16
	v_med3_f32 v8, v8, s69, v247
	v_rcp_f32_e32 v15, v15
	v_exp_f32_e32 v17, v17
	v_fma_f32 v13, v13, v8, v13
	v_fmamk_f32 v8, v148, 0x3d000000, v80
	v_med3_f32 v8, v8, s69, v247
	v_mul_f32_e32 v14, v14, v15
	v_add_f32_e32 v15, 1.0, v17
	v_fma_f32 v14, v14, v8, v14
	v_fmamk_f32 v8, v149, 0x3d000000, v81
	v_rcp_f32_e32 v15, v15
	v_med3_f32 v17, v8, s69, v247
	v_mov_b32_e32 v8, v217
	v_cvt_pk_fp8_f32 v8, v7, v9
	v_mov_b32_e32 v9, v217
	v_cvt_pk_fp8_f32 v9, v12, v13
	v_mul_f32_e32 v15, v16, v15
	v_fma_f32 v7, v15, v17, v15
	v_or_b32_e32 v6, 48, v6
	v_cvt_pk_fp8_f32 v9, v14, v7 op_sel:[0,0,1]
	v_ashrrev_i32_e32 v7, 31, v6
	v_lshlrev_b64 v[6:7], 11, v[6:7]
	v_lshl_add_u64 v[6:7], s[20:21], 0, v[6:7]
	v_lshl_add_u64 v[4:5], v[6:7], 0, v[4:5]
	v_fmamk_f32 v6, v143, 0x3d000000, v67
	v_min_f32_e32 v6, 0x40e00000, v6
	v_mul_f32_e32 v7, 0xc01d265f, v6
	v_exp_f32_e32 v7, v7
	v_cvt_pk_fp8_f32 v8, v10, v11 op_sel:[0,0,1]
	v_fmamk_f32 v10, v142, 0x3d000000, v66
	v_min_f32_e32 v10, 0x40e00000, v10
	v_add_f32_e32 v7, 1.0, v7
	v_mul_f32_e32 v11, 0xc01d265f, v10
	v_rcp_f32_e32 v7, v7
	v_exp_f32_e32 v11, v11
	global_store_dwordx2 v[4:5], v[8:9], off
	v_mul_f32_e32 v6, v6, v7
	v_fmamk_f32 v7, v144, 0x3d000000, v68
	v_min_f32_e32 v7, 0x40e00000, v7
	v_add_f32_e32 v5, 1.0, v11
	v_mul_f32_e32 v8, 0xc01d265f, v7
	v_rcp_f32_e32 v5, v5
	v_exp_f32_e32 v8, v8
	v_fmamk_f32 v9, v145, 0x3d000000, v69
	v_min_f32_e32 v9, 0x40e00000, v9
	v_mul_f32_e32 v5, v10, v5
	v_mul_f32_e32 v10, 0xc01d265f, v9
	v_add_f32_e32 v8, 1.0, v8
	v_rcp_f32_e32 v8, v8
	v_exp_f32_e32 v10, v10
	v_fmamk_f32 v11, v135, 0x3d000000, v71
	v_min_f32_e32 v11, 0x40e00000, v11
	v_mul_f32_e32 v7, v7, v8
	v_add_f32_e32 v8, 1.0, v10
	v_rcp_f32_e32 v8, v8
	v_mul_f32_e32 v12, 0xc01d265f, v11
	v_exp_f32_e32 v12, v12
	v_mul_f32_e32 v8, v9, v8
	v_fmamk_f32 v9, v134, 0x3d000000, v70
	v_min_f32_e32 v9, 0x40e00000, v9
	v_mul_f32_e32 v10, 0xc01d265f, v9
	v_exp_f32_e32 v10, v10
	v_fmamk_f32 v4, v138, 0x3d000000, v74
	v_med3_f32 v4, v4, s69, v247
	v_add_f32_e32 v10, 1.0, v10
	v_rcp_f32_e32 v10, v10
	v_fma_f32 v5, v5, v4, v5
	v_fmamk_f32 v4, v139, 0x3d000000, v75
	v_med3_f32 v4, v4, s69, v247
	v_mul_f32_e32 v9, v9, v10
	v_add_f32_e32 v10, 1.0, v12
	v_rcp_f32_e32 v10, v10
	v_fma_f32 v6, v6, v4, v6
	v_fmamk_f32 v4, v140, 0x3d000000, v76
	v_med3_f32 v4, v4, s69, v247
	v_mul_f32_e32 v10, v11, v10
	v_fmamk_f32 v11, v136, 0x3d000000, v72
	v_min_f32_e32 v11, 0x40e00000, v11
	v_fma_f32 v7, v7, v4, v7
	v_fmamk_f32 v4, v141, 0x3d000000, v77
	v_mul_f32_e32 v12, 0xc01d265f, v11
	v_med3_f32 v4, v4, s69, v247
	v_exp_f32_e32 v12, v12
	v_fma_f32 v8, v8, v4, v8
	v_fmamk_f32 v4, v130, 0x3d000000, v78
	v_med3_f32 v4, v4, s69, v247
	v_fmamk_f32 v13, v137, 0x3d000000, v73
	v_min_f32_e32 v13, 0x40e00000, v13
	v_fma_f32 v9, v9, v4, v9
	v_fmamk_f32 v4, v131, 0x3d000000, v79
	v_add_f32_e32 v12, 1.0, v12
	v_mul_f32_e32 v14, 0xc01d265f, v13
	v_med3_f32 v4, v4, s69, v247
	v_rcp_f32_e32 v12, v12
	v_exp_f32_e32 v14, v14
	v_fma_f32 v10, v10, v4, v10
	v_fmamk_f32 v4, v132, 0x3d000000, v80
	v_med3_f32 v4, v4, s69, v247
	v_mul_f32_e32 v11, v11, v12
	v_add_f32_e32 v12, 1.0, v14
	v_fma_f32 v11, v11, v4, v11
	v_fmamk_f32 v4, v133, 0x3d000000, v81
	v_rcp_f32_e32 v12, v12
	v_med3_f32 v14, v4, s69, v247
	v_mov_b32_e32 v4, v217
	v_cvt_pk_fp8_f32 v4, v5, v6
	v_mov_b32_e32 v5, v217
	v_cvt_pk_fp8_f32 v5, v9, v10
	v_mul_f32_e32 v12, v13, v12
	v_fma_f32 v6, v12, v14, v12
	v_cvt_pk_fp8_f32 v5, v11, v6 op_sel:[0,0,1]
	v_fmamk_f32 v6, v126, 0x3d000000, v66
	v_cvt_pk_fp8_f32 v4, v7, v8 op_sel:[0,0,1]
	v_min_f32_e32 v8, 0x40e00000, v6
	v_mul_f32_e32 v6, 0xc01d265f, v8
	v_exp_f32_e32 v9, v6
	v_add_co_u32_e32 v6, vcc, s70, v2
	v_fmamk_f32 v11, v119, 0x3d000000, v71
	s_nop 0
	v_addc_co_u32_e32 v7, vcc, 0, v3, vcc
	global_store_dwordx2 v[6:7], v[4:5], off
	v_fmamk_f32 v6, v127, 0x3d000000, v67
	v_min_f32_e32 v6, 0x40e00000, v6
	v_mul_f32_e32 v7, 0xc01d265f, v6
	v_exp_f32_e32 v7, v7
	v_add_f32_e32 v5, 1.0, v9
	v_rcp_f32_e32 v5, v5
	v_fmamk_f32 v9, v129, 0x3d000000, v69
	v_add_f32_e32 v7, 1.0, v7
	v_rcp_f32_e32 v7, v7
	v_mul_f32_e32 v5, v8, v5
	v_min_f32_e32 v9, 0x40e00000, v9
	v_mul_f32_e32 v10, 0xc01d265f, v9
	v_mul_f32_e32 v6, v6, v7
	v_fmamk_f32 v7, v128, 0x3d000000, v68
	v_min_f32_e32 v7, 0x40e00000, v7
	v_mul_f32_e32 v8, 0xc01d265f, v7
	v_exp_f32_e32 v8, v8
	v_exp_f32_e32 v10, v10
	v_min_f32_e32 v11, 0x40e00000, v11
	v_add_f32_e32 v8, 1.0, v8
	v_rcp_f32_e32 v8, v8
	v_mul_f32_e32 v12, 0xc01d265f, v11
	v_exp_f32_e32 v12, v12
	v_mul_f32_e32 v7, v7, v8
	v_add_f32_e32 v8, 1.0, v10
	v_rcp_f32_e32 v8, v8
	v_fmamk_f32 v4, v122, 0x3d000000, v74
	v_med3_f32 v4, v4, s69, v247
	v_mul_f32_e32 v8, v9, v8
	v_fmamk_f32 v9, v118, 0x3d000000, v70
	v_min_f32_e32 v9, 0x40e00000, v9
	v_mul_f32_e32 v10, 0xc01d265f, v9
	v_exp_f32_e32 v10, v10
	v_fma_f32 v5, v5, v4, v5
	v_fmamk_f32 v4, v123, 0x3d000000, v75
	v_med3_f32 v4, v4, s69, v247
	v_add_f32_e32 v10, 1.0, v10
	v_rcp_f32_e32 v10, v10
	v_fma_f32 v6, v6, v4, v6
	v_fmamk_f32 v4, v124, 0x3d000000, v76
	v_mul_f32_e32 v9, v9, v10
	v_add_f32_e32 v10, 1.0, v12
	v_rcp_f32_e32 v10, v10
	v_med3_f32 v4, v4, s69, v247
	v_fma_f32 v7, v7, v4, v7
	v_mul_f32_e32 v10, v11, v10
	v_fmamk_f32 v11, v120, 0x3d000000, v72
	v_min_f32_e32 v11, 0x40e00000, v11
	v_fmamk_f32 v4, v125, 0x3d000000, v77
	v_mul_f32_e32 v12, 0xc01d265f, v11
	v_med3_f32 v4, v4, s69, v247
	v_exp_f32_e32 v12, v12
	v_fma_f32 v8, v8, v4, v8
	v_fmamk_f32 v4, v114, 0x3d000000, v78
	v_med3_f32 v4, v4, s69, v247
	v_fmamk_f32 v13, v121, 0x3d000000, v73
	v_min_f32_e32 v13, 0x40e00000, v13
	v_fma_f32 v9, v9, v4, v9
	v_fmamk_f32 v4, v115, 0x3d000000, v79
	v_add_f32_e32 v12, 1.0, v12
	v_mul_f32_e32 v14, 0xc01d265f, v13
	v_med3_f32 v4, v4, s69, v247
	v_rcp_f32_e32 v12, v12
	v_exp_f32_e32 v14, v14
	v_fma_f32 v10, v10, v4, v10
	v_fmamk_f32 v4, v116, 0x3d000000, v80
	v_med3_f32 v4, v4, s69, v247
	v_mul_f32_e32 v11, v11, v12
	v_add_f32_e32 v12, 1.0, v14
	v_fma_f32 v11, v11, v4, v11
	v_fmamk_f32 v4, v117, 0x3d000000, v81
	v_rcp_f32_e32 v12, v12
	v_med3_f32 v14, v4, s69, v247
	v_mov_b32_e32 v4, v217
	v_cvt_pk_fp8_f32 v4, v5, v6
	v_mov_b32_e32 v5, v217
	v_cvt_pk_fp8_f32 v5, v9, v10
	v_mul_f32_e32 v12, v13, v12
	v_fma_f32 v6, v12, v14, v12
	v_cvt_pk_fp8_f32 v5, v11, v6 op_sel:[0,0,1]
	v_fmamk_f32 v6, v110, 0x3d000000, v66
	v_cvt_pk_fp8_f32 v4, v7, v8 op_sel:[0,0,1]
	v_min_f32_e32 v8, 0x40e00000, v6
	v_mul_f32_e32 v6, 0xc01d265f, v8
	v_exp_f32_e32 v9, v6
	v_add_co_u32_e32 v6, vcc, s71, v2
	v_fmamk_f32 v11, v103, 0x3d000000, v71
	s_nop 0
	v_addc_co_u32_e32 v7, vcc, 0, v3, vcc
	global_store_dwordx2 v[6:7], v[4:5], off
	v_fmamk_f32 v6, v111, 0x3d000000, v67
	v_min_f32_e32 v6, 0x40e00000, v6
	v_mul_f32_e32 v7, 0xc01d265f, v6
	v_exp_f32_e32 v7, v7
	v_add_f32_e32 v5, 1.0, v9
	v_rcp_f32_e32 v5, v5
	v_fmamk_f32 v9, v113, 0x3d000000, v69
	v_add_f32_e32 v7, 1.0, v7
	v_rcp_f32_e32 v7, v7
	v_mul_f32_e32 v5, v8, v5
	v_min_f32_e32 v9, 0x40e00000, v9
	v_mul_f32_e32 v10, 0xc01d265f, v9
	v_mul_f32_e32 v6, v6, v7
	v_fmamk_f32 v7, v112, 0x3d000000, v68
	v_min_f32_e32 v7, 0x40e00000, v7
	v_mul_f32_e32 v8, 0xc01d265f, v7
	v_exp_f32_e32 v8, v8
	v_exp_f32_e32 v10, v10
	v_min_f32_e32 v11, 0x40e00000, v11
	v_add_f32_e32 v8, 1.0, v8
	v_rcp_f32_e32 v8, v8
	v_mul_f32_e32 v12, 0xc01d265f, v11
	v_exp_f32_e32 v12, v12
	v_mul_f32_e32 v7, v7, v8
	v_add_f32_e32 v8, 1.0, v10
	v_rcp_f32_e32 v8, v8
	v_fmamk_f32 v4, v106, 0x3d000000, v74
	v_med3_f32 v4, v4, s69, v247
	v_mul_f32_e32 v8, v9, v8
	v_fmamk_f32 v9, v102, 0x3d000000, v70
	v_min_f32_e32 v9, 0x40e00000, v9
	v_mul_f32_e32 v10, 0xc01d265f, v9
	v_exp_f32_e32 v10, v10
	v_fma_f32 v5, v5, v4, v5
	v_fmamk_f32 v4, v107, 0x3d000000, v75
	v_med3_f32 v4, v4, s69, v247
	v_add_f32_e32 v10, 1.0, v10
	v_rcp_f32_e32 v10, v10
	v_fma_f32 v6, v6, v4, v6
	v_fmamk_f32 v4, v108, 0x3d000000, v76
	v_mul_f32_e32 v9, v9, v10
	v_add_f32_e32 v10, 1.0, v12
	v_rcp_f32_e32 v10, v10
	v_med3_f32 v4, v4, s69, v247
	v_fma_f32 v7, v7, v4, v7
	v_mul_f32_e32 v10, v11, v10
	v_fmamk_f32 v11, v104, 0x3d000000, v72
	v_min_f32_e32 v11, 0x40e00000, v11
	v_fmamk_f32 v4, v109, 0x3d000000, v77
	v_mul_f32_e32 v12, 0xc01d265f, v11
	v_med3_f32 v4, v4, s69, v247
	v_exp_f32_e32 v12, v12
	v_fma_f32 v8, v8, v4, v8
	v_fmamk_f32 v4, v98, 0x3d000000, v78
	v_med3_f32 v4, v4, s69, v247
	v_fmamk_f32 v13, v105, 0x3d000000, v73
	v_min_f32_e32 v13, 0x40e00000, v13
	v_fma_f32 v9, v9, v4, v9
	v_fmamk_f32 v4, v99, 0x3d000000, v79
	v_add_f32_e32 v12, 1.0, v12
	v_mul_f32_e32 v14, 0xc01d265f, v13
	v_med3_f32 v4, v4, s69, v247
	v_rcp_f32_e32 v12, v12
	v_exp_f32_e32 v14, v14
	v_fma_f32 v10, v10, v4, v10
	v_fmamk_f32 v4, v100, 0x3d000000, v80
	v_med3_f32 v4, v4, s69, v247
	v_mul_f32_e32 v11, v11, v12
	v_add_f32_e32 v12, 1.0, v14
	v_fma_f32 v11, v11, v4, v11
	v_fmamk_f32 v4, v101, 0x3d000000, v81
	v_rcp_f32_e32 v12, v12
	v_med3_f32 v14, v4, s69, v247
	v_mov_b32_e32 v4, v217
	v_cvt_pk_fp8_f32 v4, v5, v6
	v_mov_b32_e32 v5, v217
	v_cvt_pk_fp8_f32 v5, v9, v10
	v_mul_f32_e32 v12, v13, v12
	v_fma_f32 v6, v12, v14, v12
	v_cvt_pk_fp8_f32 v5, v11, v6 op_sel:[0,0,1]
	v_fmamk_f32 v6, v94, 0x3d000000, v66
	v_cvt_pk_fp8_f32 v4, v7, v8 op_sel:[0,0,1]
	v_min_f32_e32 v8, 0x40e00000, v6
	v_mul_f32_e32 v6, 0xc01d265f, v8
	v_exp_f32_e32 v9, v6
	v_add_co_u32_e32 v6, vcc, s72, v2
	v_fmamk_f32 v11, v87, 0x3d000000, v71
	s_nop 0
	v_addc_co_u32_e32 v7, vcc, 0, v3, vcc
	global_store_dwordx2 v[6:7], v[4:5], off
	v_fmamk_f32 v6, v95, 0x3d000000, v67
	v_min_f32_e32 v6, 0x40e00000, v6
	v_mul_f32_e32 v7, 0xc01d265f, v6
	v_exp_f32_e32 v7, v7
	v_add_f32_e32 v5, 1.0, v9
	v_rcp_f32_e32 v5, v5
	v_fmamk_f32 v9, v97, 0x3d000000, v69
	v_add_f32_e32 v7, 1.0, v7
	v_rcp_f32_e32 v7, v7
	v_mul_f32_e32 v5, v8, v5
	v_min_f32_e32 v9, 0x40e00000, v9
	v_mul_f32_e32 v10, 0xc01d265f, v9
	v_mul_f32_e32 v6, v6, v7
	v_fmamk_f32 v7, v96, 0x3d000000, v68
	v_min_f32_e32 v7, 0x40e00000, v7
	v_mul_f32_e32 v8, 0xc01d265f, v7
	v_exp_f32_e32 v8, v8
	v_exp_f32_e32 v10, v10
	v_min_f32_e32 v11, 0x40e00000, v11
	v_add_f32_e32 v8, 1.0, v8
	v_rcp_f32_e32 v8, v8
	v_mul_f32_e32 v12, 0xc01d265f, v11
	v_exp_f32_e32 v12, v12
	v_mul_f32_e32 v7, v7, v8
	v_add_f32_e32 v8, 1.0, v10
	v_rcp_f32_e32 v8, v8
	v_fmamk_f32 v4, v90, 0x3d000000, v74
	v_med3_f32 v4, v4, s69, v247
	v_mul_f32_e32 v8, v9, v8
	v_fmamk_f32 v9, v86, 0x3d000000, v70
	v_min_f32_e32 v9, 0x40e00000, v9
	v_mul_f32_e32 v10, 0xc01d265f, v9
	v_exp_f32_e32 v10, v10
	v_fma_f32 v5, v5, v4, v5
	v_fmamk_f32 v4, v91, 0x3d000000, v75
	v_med3_f32 v4, v4, s69, v247
	v_add_f32_e32 v10, 1.0, v10
	v_rcp_f32_e32 v10, v10
	v_fma_f32 v6, v6, v4, v6
	v_fmamk_f32 v4, v92, 0x3d000000, v76
	v_mul_f32_e32 v9, v9, v10
	v_add_f32_e32 v10, 1.0, v12
	v_rcp_f32_e32 v10, v10
	v_med3_f32 v4, v4, s69, v247
	v_fma_f32 v7, v7, v4, v7
	v_mul_f32_e32 v10, v11, v10
	v_fmamk_f32 v11, v88, 0x3d000000, v72
	v_min_f32_e32 v11, 0x40e00000, v11
	v_fmamk_f32 v4, v93, 0x3d000000, v77
	v_mul_f32_e32 v12, 0xc01d265f, v11
	v_med3_f32 v4, v4, s69, v247
	v_exp_f32_e32 v12, v12
	v_fma_f32 v8, v8, v4, v8
	v_fmamk_f32 v4, v82, 0x3d000000, v78
	v_med3_f32 v4, v4, s69, v247
	v_fmamk_f32 v13, v89, 0x3d000000, v73
	v_min_f32_e32 v13, 0x40e00000, v13
	v_fma_f32 v9, v9, v4, v9
	v_fmamk_f32 v4, v83, 0x3d000000, v79
	v_add_f32_e32 v12, 1.0, v12
	v_mul_f32_e32 v14, 0xc01d265f, v13
	v_med3_f32 v4, v4, s69, v247
	v_rcp_f32_e32 v12, v12
	v_exp_f32_e32 v14, v14
	v_fma_f32 v10, v10, v4, v10
	v_fmamk_f32 v4, v84, 0x3d000000, v80
	v_med3_f32 v4, v4, s69, v247
	v_mul_f32_e32 v11, v11, v12
	v_add_f32_e32 v12, 1.0, v14
	v_fma_f32 v11, v11, v4, v11
	v_fmamk_f32 v4, v85, 0x3d000000, v81
	v_rcp_f32_e32 v12, v12
	v_med3_f32 v14, v4, s69, v247
	v_mov_b32_e32 v4, v217
	v_cvt_pk_fp8_f32 v4, v5, v6
	v_mov_b32_e32 v5, v217
	v_cvt_pk_fp8_f32 v5, v9, v10
	v_mul_f32_e32 v12, v13, v12
	v_fma_f32 v6, v12, v14, v12
	v_cvt_pk_fp8_f32 v4, v7, v8 op_sel:[0,0,1]
	v_cvt_pk_fp8_f32 v5, v11, v6 op_sel:[0,0,1]
	v_add_co_u32_e32 v2, vcc, 0x58000, v2
	s_nop 1
	v_addc_co_u32_e32 v3, vcc, 0, v3, vcc
	s_and_b64 vcc, exec, s[4:5]
	s_mov_b64 s[4:5], -1
	global_store_dwordx2 v[2:3], v[4:5], off
	s_cbranch_vccnz .LBB0_1569
	s_andn2_b64 vcc, exec, s[18:19]
	s_cbranch_vccnz .LBB0_1568
	s_barrier
	s_branch .LBB0_1568
